# v49 + SwiGLU epilogue column offset formed as one 32-bit shift (sign-extension + 64-bit shift dropped)
# baseline (speedup 1.0000x reference)
; __device__ __forceinline__ unsigned pk2(float lo, float hi) { const f32x2 v = {lo, hi}; return __builtin_bit_cast(unsigned, __builtin_convertvector(v, bf16x2_t)); }
;     __device__ __forceinline__ void operator()(const f32x4 (&acc)[2][2][4][2], const Unit& u, int wr, int wc, int fr, int fq) const {
;         const int row0 = u.pm * BM + wr * 64 + fr, col0 = u.pn * HALF + wc * 32 + 8 * fq;
;         float rs8[2][4];
;         { f32x4 pa[2][4], pb[2][4];
; #pragma unroll
;           for (int ai = 0; ai < 2; ++ai)
; #pragma unroll
;             for (int m = 0; m < 4; ++m) { const float* p_ = st2 + (size_t)(row0 + ai * HALF + m * 16) * 8; pa[ai][m] = *(const f32x4*)p_; pb[ai][m] = *(const f32x4*)(p_ + 4); }
;           __builtin_amdgcn_sched_barrier(0);
; #pragma unroll
;           for (int ai = 0; ai < 2; ++ai)
; #pragma unroll
;             for (int m = 0; m < 4; ++m) { const f32x4 t_ = pa[ai][m] + pb[ai][m]; rs8[ai][m] = __builtin_amdgcn_rsqf(((t_[0] + t_[1]) + (t_[2] + t_[3])) * (1.0f / (float)D) + 1e-6f); }
;           __builtin_amdgcn_sched_barrier(0); }
; #pragma unroll
;         for (int ai = 0; ai < 2; ++ai)
; #pragma unroll
;             for (int m = 0; m < 4; ++m) {
;                 const float rs = rs8[ai][m], nrs = -1.44269504089f * rs;
;                 u32x4 w;
; #pragma unroll
;                 for (int n = 0; n < 2; ++n) { const f32x4 gq = acc[ai][0][m][n], uq = acc[ai][1][m][n];
; #pragma unroll
;                     for (int h = 0; h < 2; ++h) { const f32x2 gv = (f32x2){gq[2 * h], gq[2 * h + 1]}, uv = (f32x2){uq[2 * h], uq[2 * h + 1]};
;                         const f32x2 ea = gv * nrs; f32x2 e; e.x = __builtin_amdgcn_exp2f(ea.x); e.y = __builtin_amdgcn_exp2f(ea.y);
;                         const f32x2 d = e + 1.0f; f32x2 rc; rc.x = __builtin_amdgcn_rcpf(d.x); rc.y = __builtin_amdgcn_rcpf(d.y);
;                         const f32x2 o = (gv * uv) * (rc * (rs * rs));
;                         w[2 * n + h] = pk2(o.x, o.y); } }
;                 *(u32x4*)(O + (size_t)(row0 + ai * HALF + m * 16) * ldc + col0) = w; }
.Lmy_sw_join:
	v_lshl_or_b32 v162, s53, 7, v160
	v_mul_f32_e32 v164, 0xbfb8aa3b, v147
	v_pk_mul_f32 v[166:167], v[130:131], v[164:165] op_sel_hi:[1,0]
	v_pk_mul_f32 v[126:127], v[130:131], v[126:127]
	v_exp_f32_e32 v166, v166
	v_exp_f32_e32 v167, v167
	v_pk_mul_f32 v[130:131], v[132:133], v[164:165] op_sel_hi:[1,0]
	v_mul_f32_e32 v168, v147, v147
	v_exp_f32_e32 v130, v130
	v_exp_f32_e32 v131, v131
	v_pk_add_f32 v[166:167], v[166:167], 1.0 op_sel_hi:[1,0]
	v_pk_mul_f32 v[128:129], v[132:133], v[128:129]
	v_rcp_f32_e32 v166, v166
	v_rcp_f32_e32 v167, v167
	v_pk_add_f32 v[130:131], v[130:131], 1.0 op_sel_hi:[1,0]
	v_pk_mul_f32 v[118:119], v[122:123], v[118:119]
	v_rcp_f32_e32 v130, v130
	v_rcp_f32_e32 v131, v131
	v_pk_mul_f32 v[132:133], v[168:169], v[166:167] op_sel_hi:[0,1]
	v_pk_mul_f32 v[126:127], v[126:127], v[132:133]
	v_pk_mul_f32 v[132:133], v[122:123], v[164:165] op_sel_hi:[1,0]
	v_pk_mul_f32 v[130:131], v[168:169], v[130:131] op_sel_hi:[0,1]
	v_exp_f32_e32 v132, v132
	v_exp_f32_e32 v133, v133
	v_pk_mul_f32 v[128:129], v[128:129], v[130:131]
	v_pk_mul_f32 v[130:131], v[124:125], v[164:165] op_sel_hi:[1,0]
	v_cvt_pk_bf16_f32 v126, v126, v127
	v_exp_f32_e32 v130, v130
	v_exp_f32_e32 v131, v131
	v_cvt_pk_bf16_f32 v127, v128, v129
	v_pk_add_f32 v[128:129], v[132:133], 1.0 op_sel_hi:[1,0]
	v_pk_mul_f32 v[120:121], v[124:125], v[120:121]
	v_rcp_f32_e32 v128, v128
	v_rcp_f32_e32 v129, v129
	v_pk_add_f32 v[122:123], v[130:131], 1.0 op_sel_hi:[1,0]
	v_rcp_f32_e32 v122, v122
	v_rcp_f32_e32 v123, v123
	v_pk_mul_f32 v[124:125], v[168:169], v[128:129] op_sel_hi:[0,1]
	v_pk_mul_f32 v[118:119], v[118:119], v[124:125]
	v_mul_f32_e32 v124, 0xbfb8aa3b, v149
	v_cvt_pk_bf16_f32 v128, v118, v119
	v_pk_mul_f32 v[118:119], v[168:169], v[122:123] op_sel_hi:[0,1]
	v_pk_mul_f32 v[130:131], v[114:115], v[124:125] op_sel_hi:[1,0]
	v_pk_mul_f32 v[118:119], v[120:121], v[118:119]
	v_exp_f32_e32 v130, v130
	v_exp_f32_e32 v131, v131
	v_cvt_pk_bf16_f32 v129, v118, v119
	v_pk_mul_f32 v[110:111], v[114:115], v[110:111]
	v_pk_mul_f32 v[114:115], v[116:117], v[124:125] op_sel_hi:[1,0]
	v_lshlrev_b32_e32 v120, 1, v162
	v_exp_f32_e32 v114, v114
	v_exp_f32_e32 v115, v115
	v_mad_u32_u24 v122, v156, s1, v120
	global_store_dwordx4 v122, v[126:129], s[12:13]
	v_mul_f32_e32 v122, v149, v149
	v_pk_add_f32 v[114:115], v[114:115], 1.0 op_sel_hi:[1,0]
	v_pk_add_f32 v[126:127], v[130:131], 1.0 op_sel_hi:[1,0]
	v_rcp_f32_e32 v114, v114
	v_rcp_f32_e32 v126, v126
	v_rcp_f32_e32 v127, v127
	v_rcp_f32_e32 v115, v115
	v_pk_mul_f32 v[112:113], v[116:117], v[112:113]
	v_pk_mul_f32 v[102:103], v[106:107], v[102:103]
	v_pk_mul_f32 v[116:117], v[122:123], v[126:127] op_sel_hi:[0,1]
	v_pk_mul_f32 v[110:111], v[110:111], v[116:117]
	v_pk_mul_f32 v[116:117], v[106:107], v[124:125] op_sel_hi:[1,0]
	v_pk_mul_f32 v[114:115], v[122:123], v[114:115] op_sel_hi:[0,1]
	v_exp_f32_e32 v116, v116
	v_exp_f32_e32 v117, v117
	v_pk_mul_f32 v[112:113], v[112:113], v[114:115]
	v_pk_mul_f32 v[114:115], v[108:109], v[124:125] op_sel_hi:[1,0]
	v_cvt_pk_bf16_f32 v110, v110, v111
	v_exp_f32_e32 v114, v114
	v_exp_f32_e32 v115, v115
	v_cvt_pk_bf16_f32 v111, v112, v113
	v_pk_add_f32 v[112:113], v[116:117], 1.0 op_sel_hi:[1,0]
	v_pk_mul_f32 v[104:105], v[108:109], v[104:105]
	v_rcp_f32_e32 v112, v112
	v_rcp_f32_e32 v113, v113
	v_pk_add_f32 v[106:107], v[114:115], 1.0 op_sel_hi:[1,0]
	v_pk_mul_f32 v[94:95], v[98:99], v[94:95]
	v_rcp_f32_e32 v106, v106
	v_rcp_f32_e32 v107, v107
	v_pk_mul_f32 v[108:109], v[122:123], v[112:113] op_sel_hi:[0,1]
	v_pk_mul_f32 v[102:103], v[102:103], v[108:109]
	v_pk_mul_f32 v[96:97], v[100:101], v[96:97]
	v_cvt_pk_bf16_f32 v112, v102, v103
	v_pk_mul_f32 v[102:103], v[122:123], v[106:107] op_sel_hi:[0,1]
	v_pk_mul_f32 v[102:103], v[104:105], v[102:103]
	v_mul_f32_e32 v104, 0xbfb8aa3b, v151
	v_pk_mul_f32 v[106:107], v[98:99], v[104:105] op_sel_hi:[1,0]
	v_pk_mul_f32 v[98:99], v[100:101], v[104:105] op_sel_hi:[1,0]
	v_exp_f32_e32 v106, v106
	v_exp_f32_e32 v107, v107
	v_exp_f32_e32 v98, v98
	v_exp_f32_e32 v99, v99
	v_cvt_pk_bf16_f32 v113, v102, v103
	v_pk_add_f32 v[106:107], v[106:107], 1.0 op_sel_hi:[1,0]
	v_mad_u32_u24 v102, v154, s1, v120
	v_rcp_f32_e32 v106, v106
	v_rcp_f32_e32 v107, v107
	v_pk_add_f32 v[98:99], v[98:99], 1.0 op_sel_hi:[1,0]
	v_rcp_f32_e32 v98, v98
	v_rcp_f32_e32 v99, v99
	global_store_dwordx4 v102, v[110:113], s[12:13]
	v_mul_f32_e32 v102, v151, v151
	v_pk_mul_f32 v[100:101], v[102:103], v[106:107] op_sel_hi:[0,1]
	v_pk_mul_f32 v[94:95], v[94:95], v[100:101]
	v_pk_mul_f32 v[100:101], v[90:91], v[104:105] op_sel_hi:[1,0]
	v_pk_mul_f32 v[98:99], v[102:103], v[98:99] op_sel_hi:[0,1]
	v_exp_f32_e32 v100, v100
	v_exp_f32_e32 v101, v101
	v_pk_mul_f32 v[96:97], v[96:97], v[98:99]
	v_pk_mul_f32 v[98:99], v[92:93], v[104:105] op_sel_hi:[1,0]
	v_cvt_pk_bf16_f32 v94, v94, v95
	v_exp_f32_e32 v98, v98
	v_exp_f32_e32 v99, v99
	v_cvt_pk_bf16_f32 v95, v96, v97
	v_pk_add_f32 v[96:97], v[100:101], 1.0 op_sel_hi:[1,0]
	v_pk_mul_f32 v[86:87], v[90:91], v[86:87]
	v_rcp_f32_e32 v96, v96
	v_rcp_f32_e32 v97, v97
	v_pk_add_f32 v[90:91], v[98:99], 1.0 op_sel_hi:[1,0]
	v_pk_mul_f32 v[88:89], v[92:93], v[88:89]
	v_rcp_f32_e32 v90, v90
	v_rcp_f32_e32 v91, v91
	v_pk_mul_f32 v[92:93], v[102:103], v[96:97] op_sel_hi:[0,1]
	v_pk_mul_f32 v[86:87], v[86:87], v[92:93]
	v_pk_mul_f32 v[78:79], v[82:83], v[78:79]
	v_cvt_pk_bf16_f32 v96, v86, v87
	v_pk_mul_f32 v[86:87], v[102:103], v[90:91] op_sel_hi:[0,1]
	v_pk_mul_f32 v[86:87], v[88:89], v[86:87]
	v_mul_f32_e32 v88, 0xbfb8aa3b, v153
	v_pk_mul_f32 v[90:91], v[82:83], v[88:89] op_sel_hi:[1,0]
	v_pk_mul_f32 v[82:83], v[84:85], v[88:89] op_sel_hi:[1,0]
; __device__ __forceinline__ unsigned pk2(float lo, float hi) { const f32x2 v = {lo, hi}; return __builtin_bit_cast(unsigned, __builtin_convertvector(v, bf16x2_t)); }
;     __device__ __forceinline__ void operator()(const f32x4 (&acc)[2][2][4][2], const Unit& u, int wr, int wc, int fr, int fq) const {
;     ...
;             for (int m = 0; m < 4; ++m) {
;                 const float rs = rs8[ai][m], nrs = -1.44269504089f * rs;
;                 u32x4 w;
; #pragma unroll
;                 for (int n = 0; n < 2; ++n) { const f32x4 gq = acc[ai][0][m][n], uq = acc[ai][1][m][n];
; #pragma unroll
;                     for (int h = 0; h < 2; ++h) { const f32x2 gv = (f32x2){gq[2 * h], gq[2 * h + 1]}, uv = (f32x2){uq[2 * h], uq[2 * h + 1]};
;                         const f32x2 ea = gv * nrs; f32x2 e; e.x = __builtin_amdgcn_exp2f(ea.x); e.y = __builtin_amdgcn_exp2f(ea.y);
;                         const f32x2 d = e + 1.0f; f32x2 rc; rc.x = __builtin_amdgcn_rcpf(d.x); rc.y = __builtin_amdgcn_rcpf(d.y);
;                         const f32x2 o = (gv * uv) * (rc * (rs * rs));
;                         w[2 * n + h] = pk2(o.x, o.y); } }
;                 *(u32x4*)(O + (size_t)(row0 + ai * HALF + m * 16) * ldc + col0) = w; }
	v_exp_f32_e32 v90, v90
	v_exp_f32_e32 v91, v91
	v_exp_f32_e32 v82, v82
	v_exp_f32_e32 v83, v83
	v_cvt_pk_bf16_f32 v97, v86, v87
	v_pk_add_f32 v[90:91], v[90:91], 1.0 op_sel_hi:[1,0]
	v_mad_u32_u24 v86, v152, s1, v120
	v_rcp_f32_e32 v90, v90
	v_rcp_f32_e32 v91, v91
	v_pk_add_f32 v[82:83], v[82:83], 1.0 op_sel_hi:[1,0]
	v_rcp_f32_e32 v82, v82
	v_rcp_f32_e32 v83, v83
	global_store_dwordx4 v86, v[94:97], s[12:13]
	v_mul_f32_e32 v86, v153, v153
	v_pk_mul_f32 v[80:81], v[84:85], v[80:81]
	v_pk_mul_f32 v[84:85], v[86:87], v[90:91] op_sel_hi:[0,1]
	v_pk_mul_f32 v[78:79], v[78:79], v[84:85]
	v_pk_mul_f32 v[84:85], v[74:75], v[88:89] op_sel_hi:[1,0]
	v_pk_mul_f32 v[82:83], v[86:87], v[82:83] op_sel_hi:[0,1]
	v_exp_f32_e32 v84, v84
	v_exp_f32_e32 v85, v85
	v_pk_mul_f32 v[80:81], v[80:81], v[82:83]
	v_pk_mul_f32 v[82:83], v[76:77], v[88:89] op_sel_hi:[1,0]
	v_cvt_pk_bf16_f32 v78, v78, v79
	v_exp_f32_e32 v82, v82
	v_exp_f32_e32 v83, v83
	v_cvt_pk_bf16_f32 v79, v80, v81
	v_pk_add_f32 v[80:81], v[84:85], 1.0 op_sel_hi:[1,0]
	v_pk_mul_f32 v[70:71], v[74:75], v[70:71]
	v_rcp_f32_e32 v80, v80
	v_rcp_f32_e32 v81, v81
	v_pk_add_f32 v[74:75], v[82:83], 1.0 op_sel_hi:[1,0]
	v_pk_mul_f32 v[72:73], v[76:77], v[72:73]
	v_rcp_f32_e32 v74, v74
	v_rcp_f32_e32 v75, v75
	v_pk_mul_f32 v[76:77], v[86:87], v[80:81] op_sel_hi:[0,1]
	v_pk_mul_f32 v[70:71], v[70:71], v[76:77]
	v_pk_mul_f32 v[62:63], v[66:67], v[62:63]
	v_cvt_pk_bf16_f32 v80, v70, v71
	v_pk_mul_f32 v[70:71], v[86:87], v[74:75] op_sel_hi:[0,1]
	v_pk_mul_f32 v[70:71], v[72:73], v[70:71]
	v_mul_f32_e32 v72, 0xbfb8aa3b, v155
	v_pk_mul_f32 v[74:75], v[66:67], v[72:73] op_sel_hi:[1,0]
	v_pk_mul_f32 v[66:67], v[68:69], v[72:73] op_sel_hi:[1,0]
	v_exp_f32_e32 v74, v74
	v_exp_f32_e32 v75, v75
	v_exp_f32_e32 v66, v66
	v_exp_f32_e32 v67, v67
	v_cvt_pk_bf16_f32 v81, v70, v71
	v_pk_add_f32 v[74:75], v[74:75], 1.0 op_sel_hi:[1,0]
	v_mad_u32_u24 v70, v150, s1, v120
	v_rcp_f32_e32 v74, v74
	v_rcp_f32_e32 v75, v75
	v_pk_add_f32 v[66:67], v[66:67], 1.0 op_sel_hi:[1,0]
	v_rcp_f32_e32 v66, v66
	v_rcp_f32_e32 v67, v67
	global_store_dwordx4 v70, v[78:81], s[12:13]
	v_mul_f32_e32 v70, v155, v155
	v_pk_mul_f32 v[64:65], v[68:69], v[64:65]
	v_pk_mul_f32 v[68:69], v[70:71], v[74:75] op_sel_hi:[0,1]
	v_pk_mul_f32 v[62:63], v[62:63], v[68:69]
	v_pk_mul_f32 v[68:69], v[58:59], v[72:73] op_sel_hi:[1,0]
	v_pk_mul_f32 v[66:67], v[70:71], v[66:67] op_sel_hi:[0,1]
	v_exp_f32_e32 v68, v68
	v_exp_f32_e32 v69, v69
	v_pk_mul_f32 v[64:65], v[64:65], v[66:67]
	v_pk_mul_f32 v[66:67], v[60:61], v[72:73] op_sel_hi:[1,0]
	v_cvt_pk_bf16_f32 v62, v62, v63
	v_exp_f32_e32 v66, v66
	v_exp_f32_e32 v67, v67
	v_cvt_pk_bf16_f32 v63, v64, v65
	v_pk_add_f32 v[64:65], v[68:69], 1.0 op_sel_hi:[1,0]
	v_pk_mul_f32 v[54:55], v[58:59], v[54:55]
	v_rcp_f32_e32 v64, v64
	v_rcp_f32_e32 v65, v65
	v_pk_add_f32 v[58:59], v[66:67], 1.0 op_sel_hi:[1,0]
	v_pk_mul_f32 v[56:57], v[60:61], v[56:57]
	v_rcp_f32_e32 v58, v58
	v_rcp_f32_e32 v59, v59
	v_pk_mul_f32 v[60:61], v[70:71], v[64:65] op_sel_hi:[0,1]
	v_pk_mul_f32 v[54:55], v[54:55], v[60:61]
	v_pk_mul_f32 v[46:47], v[50:51], v[46:47]
	v_cvt_pk_bf16_f32 v64, v54, v55
	v_pk_mul_f32 v[54:55], v[70:71], v[58:59] op_sel_hi:[0,1]
	v_pk_mul_f32 v[54:55], v[56:57], v[54:55]
	v_mul_f32_e32 v56, 0xbfb8aa3b, v157
	v_pk_mul_f32 v[58:59], v[50:51], v[56:57] op_sel_hi:[1,0]
	v_pk_mul_f32 v[50:51], v[52:53], v[56:57] op_sel_hi:[1,0]
	v_exp_f32_e32 v58, v58
	v_exp_f32_e32 v59, v59
	v_exp_f32_e32 v50, v50
	v_exp_f32_e32 v51, v51
	v_cvt_pk_bf16_f32 v65, v54, v55
	v_pk_add_f32 v[58:59], v[58:59], 1.0 op_sel_hi:[1,0]
	v_mad_u32_u24 v54, v148, s1, v120
	v_rcp_f32_e32 v58, v58
	v_rcp_f32_e32 v59, v59
	v_pk_add_f32 v[50:51], v[50:51], 1.0 op_sel_hi:[1,0]
	v_rcp_f32_e32 v50, v50
	v_rcp_f32_e32 v51, v51
	global_store_dwordx4 v54, v[62:65], s[12:13]
	v_mul_f32_e32 v54, v157, v157
	v_pk_mul_f32 v[48:49], v[52:53], v[48:49]
	v_pk_mul_f32 v[52:53], v[54:55], v[58:59] op_sel_hi:[0,1]
	v_pk_mul_f32 v[46:47], v[46:47], v[52:53]
	v_pk_mul_f32 v[52:53], v[42:43], v[56:57] op_sel_hi:[1,0]
	v_pk_mul_f32 v[50:51], v[54:55], v[50:51] op_sel_hi:[0,1]
	v_exp_f32_e32 v52, v52
	v_exp_f32_e32 v53, v53
	v_pk_mul_f32 v[48:49], v[48:49], v[50:51]
	v_pk_mul_f32 v[50:51], v[44:45], v[56:57] op_sel_hi:[1,0]
	v_cvt_pk_bf16_f32 v46, v46, v47
; __device__ __forceinline__ unsigned pk2(float lo, float hi) { const f32x2 v = {lo, hi}; return __builtin_bit_cast(unsigned, __builtin_convertvector(v, bf16x2_t)); }
; #define PG8_BAR __builtin_amdgcn_s_barrier()
;     __device__ __forceinline__ void operator()(const f32x4 (&acc)[2][2][4][2], const Unit& u, int wr, int wc, int fr, int fq) const {
;     ...
;             for (int m = 0; m < 4; ++m) {
;                 const float rs = rs8[ai][m], nrs = -1.44269504089f * rs;
;                 u32x4 w;
; #pragma unroll
;                 for (int n = 0; n < 2; ++n) { const f32x4 gq = acc[ai][0][m][n], uq = acc[ai][1][m][n];
; #pragma unroll
;                     for (int h = 0; h < 2; ++h) { const f32x2 gv = (f32x2){gq[2 * h], gq[2 * h + 1]}, uv = (f32x2){uq[2 * h], uq[2 * h + 1]};
;                         const f32x2 ea = gv * nrs; f32x2 e; e.x = __builtin_amdgcn_exp2f(ea.x); e.y = __builtin_amdgcn_exp2f(ea.y);
;                         const f32x2 d = e + 1.0f; f32x2 rc; rc.x = __builtin_amdgcn_rcpf(d.x); rc.y = __builtin_amdgcn_rcpf(d.y);
;                         const f32x2 o = (gv * uv) * (rc * (rs * rs));
;                         w[2 * n + h] = pk2(o.x, o.y); } }
;                 *(u32x4*)(O + (size_t)(row0 + ai * HALF + m * 16) * ldc + col0) = w; }
; template <class Epi, class Sched>
; __device__ __forceinline__ void gemm_phase(LAS unsigned char* lds, const Gemm g, const Sched& S, const Epi& E) {
;     ...
;         if constexpr (!Epi::AFTER_DRAIN) { E(acc, cur, wr, wc, fr, fq); S.done(cur); }
;         if (!has_next) break;
; #pragma unroll
;         for (int a = 0; a < 2; ++a)
; #pragma unroll
;             for (int b = 0; b < 2; ++b)
; #pragma unroll
;                 for (int m = 0; m < 4; ++m)
; #pragma unroll
;                     for (int n = 0; n < 2; ++n) acc[a][b][m][n] = (f32x4){0.f, 0.f, 0.f, 0.f};
;         cur = nxt; cA = nA; cB = nB; ++ui;
;         if (wr == 1) PG8_BAR;
	v_exp_f32_e32 v50, v50
	v_exp_f32_e32 v51, v51
	v_cvt_pk_bf16_f32 v47, v48, v49
	v_pk_add_f32 v[48:49], v[52:53], 1.0 op_sel_hi:[1,0]
	v_pk_mul_f32 v[38:39], v[42:43], v[38:39]
	v_rcp_f32_e32 v48, v48
	v_rcp_f32_e32 v49, v49
	v_pk_add_f32 v[42:43], v[50:51], 1.0 op_sel_hi:[1,0]
	v_pk_mul_f32 v[40:41], v[44:45], v[40:41]
	v_rcp_f32_e32 v42, v42
	v_rcp_f32_e32 v43, v43
	v_pk_mul_f32 v[44:45], v[54:55], v[48:49] op_sel_hi:[0,1]
	v_pk_mul_f32 v[38:39], v[38:39], v[44:45]
	v_pk_mul_f32 v[30:31], v[34:35], v[30:31]
	v_cvt_pk_bf16_f32 v48, v38, v39
	v_pk_mul_f32 v[38:39], v[54:55], v[42:43] op_sel_hi:[0,1]
	v_pk_mul_f32 v[38:39], v[40:41], v[38:39]
	v_mul_f32_e32 v40, 0xbfb8aa3b, v145
	v_pk_mul_f32 v[42:43], v[34:35], v[40:41] op_sel_hi:[1,0]
	v_pk_mul_f32 v[34:35], v[36:37], v[40:41] op_sel_hi:[1,0]
	v_exp_f32_e32 v42, v42
	v_exp_f32_e32 v43, v43
	v_exp_f32_e32 v34, v34
	v_exp_f32_e32 v35, v35
	v_cvt_pk_bf16_f32 v49, v38, v39
	v_pk_add_f32 v[42:43], v[42:43], 1.0 op_sel_hi:[1,0]
	v_mad_u32_u24 v38, v146, s1, v120
	v_rcp_f32_e32 v42, v42
	v_rcp_f32_e32 v43, v43
	v_pk_add_f32 v[34:35], v[34:35], 1.0 op_sel_hi:[1,0]
	v_rcp_f32_e32 v34, v34
	v_rcp_f32_e32 v35, v35
	global_store_dwordx4 v38, v[46:49], s[12:13]
	v_mul_f32_e32 v38, v145, v145
	v_pk_mul_f32 v[32:33], v[36:37], v[32:33]
	v_pk_mul_f32 v[36:37], v[38:39], v[42:43] op_sel_hi:[0,1]
	v_pk_mul_f32 v[30:31], v[30:31], v[36:37]
	v_pk_mul_f32 v[36:37], v[26:27], v[40:41] op_sel_hi:[1,0]
	v_pk_mul_f32 v[34:35], v[38:39], v[34:35] op_sel_hi:[0,1]
	v_exp_f32_e32 v36, v36
	v_exp_f32_e32 v37, v37
	v_pk_mul_f32 v[32:33], v[32:33], v[34:35]
	v_pk_mul_f32 v[34:35], v[28:29], v[40:41] op_sel_hi:[1,0]
	v_cvt_pk_bf16_f32 v30, v30, v31
	v_exp_f32_e32 v34, v34
	v_exp_f32_e32 v35, v35
	v_cvt_pk_bf16_f32 v31, v32, v33
	v_pk_add_f32 v[32:33], v[36:37], 1.0 op_sel_hi:[1,0]
	v_pk_mul_f32 v[22:23], v[26:27], v[22:23]
	v_rcp_f32_e32 v32, v32
	v_rcp_f32_e32 v33, v33
	v_pk_add_f32 v[26:27], v[34:35], 1.0 op_sel_hi:[1,0]
	v_pk_mul_f32 v[24:25], v[28:29], v[24:25]
	v_rcp_f32_e32 v26, v26
	v_rcp_f32_e32 v27, v27
	v_pk_mul_f32 v[28:29], v[38:39], v[32:33] op_sel_hi:[0,1]
	v_pk_mul_f32 v[22:23], v[22:23], v[28:29]
	v_pk_mul_f32 v[14:15], v[18:19], v[14:15]
	v_cvt_pk_bf16_f32 v32, v22, v23
	v_pk_mul_f32 v[22:23], v[38:39], v[26:27] op_sel_hi:[0,1]
	v_pk_mul_f32 v[22:23], v[24:25], v[22:23]
	v_mul_f32_e32 v24, 0xbfb8aa3b, v143
	v_pk_mul_f32 v[26:27], v[18:19], v[24:25] op_sel_hi:[1,0]
	v_pk_mul_f32 v[18:19], v[20:21], v[24:25] op_sel_hi:[1,0]
	v_exp_f32_e32 v26, v26
	v_exp_f32_e32 v27, v27
	v_exp_f32_e32 v18, v18
	v_exp_f32_e32 v19, v19
	v_cvt_pk_bf16_f32 v33, v22, v23
	v_pk_add_f32 v[26:27], v[26:27], 1.0 op_sel_hi:[1,0]
	v_mad_u32_u24 v22, v144, s1, v120
	v_rcp_f32_e32 v26, v26
	v_rcp_f32_e32 v27, v27
	v_pk_add_f32 v[18:19], v[18:19], 1.0 op_sel_hi:[1,0]
	v_rcp_f32_e32 v18, v18
	v_rcp_f32_e32 v19, v19
	global_store_dwordx4 v22, v[30:33], s[12:13]
	v_mul_f32_e32 v22, v143, v143
	v_pk_mul_f32 v[16:17], v[20:21], v[16:17]
	v_pk_mul_f32 v[20:21], v[22:23], v[26:27] op_sel_hi:[0,1]
	v_pk_mul_f32 v[14:15], v[14:15], v[20:21]
	v_pk_mul_f32 v[20:21], v[10:11], v[24:25] op_sel_hi:[1,0]
	v_pk_mul_f32 v[18:19], v[22:23], v[18:19] op_sel_hi:[0,1]
	v_exp_f32_e32 v20, v20
	v_exp_f32_e32 v21, v21
	v_pk_mul_f32 v[16:17], v[16:17], v[18:19]
	v_pk_mul_f32 v[18:19], v[12:13], v[24:25] op_sel_hi:[1,0]
	v_cvt_pk_bf16_f32 v14, v14, v15
	v_exp_f32_e32 v18, v18
	v_exp_f32_e32 v19, v19
	v_cvt_pk_bf16_f32 v15, v16, v17
	v_pk_add_f32 v[16:17], v[20:21], 1.0 op_sel_hi:[1,0]
	v_pk_mul_f32 v[6:7], v[10:11], v[6:7]
	v_rcp_f32_e32 v16, v16
	v_rcp_f32_e32 v17, v17
	v_pk_add_f32 v[10:11], v[18:19], 1.0 op_sel_hi:[1,0]
	v_pk_mul_f32 v[8:9], v[12:13], v[8:9]
	v_rcp_f32_e32 v10, v10
	v_rcp_f32_e32 v11, v11
	v_pk_mul_f32 v[12:13], v[22:23], v[16:17] op_sel_hi:[0,1]
	v_pk_mul_f32 v[6:7], v[6:7], v[12:13]
	s_andn2_b64 vcc, exec, s[38:39]
	v_cvt_pk_bf16_f32 v16, v6, v7
	v_pk_mul_f32 v[6:7], v[22:23], v[10:11] op_sel_hi:[0,1]
	v_pk_mul_f32 v[6:7], v[8:9], v[6:7]
	s_nop 0
	v_cvt_pk_bf16_f32 v17, v6, v7
	v_mad_u32_u24 v6, v142, s1, v120
	s_mov_b64 s[26:27], -1
	global_store_dwordx4 v6, v[14:17], s[12:13]
	s_cbranch_vccnz .LBB0_133
	s_andn2_b64 vcc, exec, s[10:11]
	s_cbranch_vccnz .LBB0_132
	s_barrier
	s_branch .LBB0_132

; #define PG8_STAGE(bufoff, gbase, voff) do { _Pragma("unroll") for (int _i = 0; _i < 2; ++_i) \
;         __builtin_amdgcn_global_load_lds((const unsigned*)((const char*)(gbase) + (voff)[_i]), (LAS unsigned*)(lds + (bufoff) + ldsw + _i * 8192), 16, 0, 0); } while (0)
; #define PG8_WAIT_V(n) asm volatile("s_waitcnt vmcnt(" #n ")" ::: "memory")
; #define PG8_BAR __builtin_amdgcn_s_barrier()
; template <class Epi, class Sched>
; __device__ __forceinline__ void gemm_phase(LAS unsigned char* lds, const Gemm g, const Sched& S, const Epi& E) {
;     ...
;     for (int i = 0; i < 2; ++i) { int R, C; stage_rc(tid * 16 + i * 8192, R, C); const int Rb = Epi::PERM ? ((R & ~31) + perm32(R & 31)) : R;
;         voffA[i] = (unsigned)(R * g.lda + C) * 2u; voffB[i] = (unsigned)(Rb * g.ldb + C) * 2u; }
;     const size_t kstep = (size_t)(BK * 2);
;     const size_t hstepA = (size_t)HALF * g.lda * 2, hstepB = (size_t)HALF * g.ldb * 2;
;     const size_t tstepA = 2 * hstepA, tstepB = 2 * hstepB;
;     const unsigned ldsw = (unsigned)wid * 1024u;
;     const int aoff = lds_byte(wr * 64 + fr, fq * 8), boff = lds_byte(wc * 32 + fr, fq * 8);
;     ...
;     Unit cur, nxt; int ui = 0;
;     if (!S.next(0, cur)) return;
;     f32x4 acc[2][2][4][2];
; #pragma unroll
;     for (int a = 0; a < 2; ++a)
; #pragma unroll
;         for (int b = 0; b < 2; ++b)
; #pragma unroll
;             for (int m = 0; m < 4; ++m)
; #pragma unroll
;                 for (int n = 0; n < 2; ++n) acc[a][b][m][n] = (f32x4){0.f, 0.f, 0.f, 0.f};
;     bf16x8 At[4][2], B0[2][2], B1[2][2];
;     const char* cA = (const char*)g.A + (size_t)cur.pm * tstepA + (size_t)cur.ka * 2; const char* cB = (const char*)g.Bt + (size_t)cur.pn * tstepB;
;     S.a_ready(cur);
;     PG8_STAGE(PG8_SB(0, 0), cB, voffB); PG8_STAGE(PG8_SB(0, 1), cB + hstepB, voffB); PG8_STAGE(PG8_SA(0, 0), cA, voffA); PG8_STAGE(PG8_SA(0, 1), cA + hstepA, voffA);
;     if (wr == 1) PG8_BAR;
;     PG8_WAIT_V(2); PG8_BAR;
;     PG8_STAGE(PG8_SB(1, 0), cB + kstep, voffB); PG8_STAGE(PG8_SA(1, 0), cA + kstep, voffA); PG8_STAGE(PG8_SB(1, 1), cB + hstepB + kstep, voffB);
;     PG8_WAIT_V(6); PG8_BAR;
.LBB0_267:
	v_lshl_add_u64 v[14:15], s[24:25], 0, v[4:5]
	v_mov_b32_e32 v3, v5
	v_and_b32_e32 v142, 15, v143
	v_and_b32_e32 v22, 48, v143
	v_lshlrev_b32_e32 v23, 2, v143
	v_lshl_add_u64 v[16:17], s[24:25], 0, v[2:3]
	s_and_b32 s48, s44, 3
	v_lshl_or_b32 v22, v142, 6, v22
	s_lshl_b32 s4, s47, 13
	v_and_b32_e32 v23, 32, v23
	s_add_i32 m0, s50, 0x18000
	v_lshl_add_u64 v[14:15], v[14:15], 0, s[36:37]
	v_lshl_add_u64 v[18:19], s[20:21], 0, v[4:5]
	v_bitop3_b32 v24, v22, s4, v23 bitop3:0xde
	s_lshl_b32 s4, s48, 12
	s_waitcnt vmcnt(2)
	s_barrier
	global_load_lds_dwordx4 v[14:15], off
	v_lshl_add_u64 v[14:15], v[16:17], 0, s[36:37]
	s_add_i32 m0, s50, 0x1a000
	s_add_i32 s54, s50, 0x8000
	s_add_i32 s55, s50, 0xa000
	v_lshl_add_u64 v[20:21], s[20:21], 0, v[2:3]
	v_bitop3_b32 v144, v22, s4, v23 bitop3:0xde
	global_load_lds_dwordx4 v[14:15], off
	v_lshl_add_u64 v[14:15], v[18:19], 0, s[36:37]
	s_mov_b32 m0, s54
	s_add_u32 s4, s24, 0x158080
	global_load_lds_dwordx4 v[14:15], off
	v_lshl_add_u64 v[14:15], v[20:21], 0, s[36:37]
	s_mov_b32 m0, s55
	s_addc_u32 s5, s25, 0
	global_load_lds_dwordx4 v[14:15], off
	s_add_i32 m0, s50, 0x1c000
	v_lshl_add_u64 v[14:15], s[4:5], 0, v[4:5]
	global_load_lds_dwordx4 v[14:15], off
	v_lshl_add_u64 v[14:15], s[4:5], 0, v[2:3]
	s_add_i32 m0, s50, 0x1e000
	s_movk_i32 s10, 0x1580
	global_load_lds_dwordx4 v[14:15], off
	v_lshrrev_b32_e32 v11, 1, v11
	v_mul_lo_u32 v10, v10, s10
	s_mov_b32 s22, 0x15800
	v_mad_u64_u32 v[10:11], s[4:5], v11, s22, v[10:11]
	v_or_b32_e32 v10, v10, v12
	v_add_lshl_u32 v134, v10, v13, 1
	v_lshrrev_b32_e32 v10, 1, v6
	v_mul_lo_u32 v6, v7, s10
	v_mad_u64_u32 v[6:7], s[4:5], v10, s22, v[6:7]
	s_waitcnt vmcnt(6)
	v_or_b32_e32 v6, v6, v8
	s_cmpk_lt_u32 s45, 0x100
	v_add_lshl_u32 v136, v6, v9, 1
	v_mov_b32_e32 v6, 0
	v_readlane_b32 s4, v254, 13
	s_cselect_b64 s[18:19], -1, 0
	v_mov_b32_e32 v135, v5
	v_mov_b32_e32 v137, v5
	s_mov_b32 s59, 0
	v_add_u32_e32 v145, 0, v24
	s_mov_b32 s10, s4
	v_readlane_b32 s46, v253, 61
	v_mov_b32_e32 v7, v6
	v_mov_b32_e32 v8, v6
	v_mov_b32_e32 v9, v6
	v_mov_b32_e32 v10, v6
	v_mov_b32_e32 v11, v6
	v_mov_b32_e32 v12, v6
	v_mov_b32_e32 v13, v6
	v_mov_b32_e32 v14, v6
	v_mov_b32_e32 v15, v6
	v_mov_b32_e32 v16, v6
	v_mov_b32_e32 v17, v6
	v_mov_b32_e32 v18, v6
	v_mov_b32_e32 v19, v6
	v_mov_b32_e32 v20, v6
	v_mov_b32_e32 v21, v6
	v_mov_b32_e32 v22, v6
	v_mov_b32_e32 v23, v6
	v_mov_b32_e32 v24, v6
	v_mov_b32_e32 v25, v6
	v_mov_b32_e32 v30, v6
	v_mov_b32_e32 v31, v6
	v_mov_b32_e32 v32, v6
	v_mov_b32_e32 v33, v6
	v_mov_b32_e32 v38, v6
	v_mov_b32_e32 v39, v6
	v_mov_b32_e32 v40, v6
	v_mov_b32_e32 v41, v6
	v_mov_b32_e32 v46, v6
	v_mov_b32_e32 v47, v6
	v_mov_b32_e32 v48, v6
	v_mov_b32_e32 v49, v6
	v_mov_b32_e32 v26, v6
	v_mov_b32_e32 v27, v6
	v_mov_b32_e32 v28, v6
	v_mov_b32_e32 v29, v6
	v_mov_b32_e32 v34, v6
	v_mov_b32_e32 v35, v6
	v_mov_b32_e32 v36, v6
	v_mov_b32_e32 v37, v6
	v_mov_b32_e32 v42, v6
	v_mov_b32_e32 v43, v6
	v_mov_b32_e32 v44, v6
	v_mov_b32_e32 v45, v6
	v_mov_b32_e32 v50, v6
	v_mov_b32_e32 v51, v6
	v_mov_b32_e32 v52, v6
	v_mov_b32_e32 v53, v6
	v_mov_b32_e32 v54, v6
	v_mov_b32_e32 v55, v6
	v_mov_b32_e32 v56, v6
	v_mov_b32_e32 v57, v6
	v_mov_b32_e32 v58, v6
	v_mov_b32_e32 v59, v6
	v_mov_b32_e32 v60, v6
	v_mov_b32_e32 v61, v6
	v_mov_b32_e32 v62, v6
	v_mov_b32_e32 v63, v6
	v_mov_b32_e32 v64, v6
	v_mov_b32_e32 v65, v6
	v_mov_b32_e32 v66, v6
	v_mov_b32_e32 v67, v6
	v_mov_b32_e32 v68, v6
	v_mov_b32_e32 v69, v6
	v_mov_b32_e32 v70, v6
	v_mov_b32_e32 v71, v6
	v_mov_b32_e32 v72, v6
	v_mov_b32_e32 v73, v6
	v_mov_b32_e32 v74, v6
	v_mov_b32_e32 v75, v6
	v_mov_b32_e32 v76, v6
	v_mov_b32_e32 v77, v6
	v_mov_b32_e32 v78, v6
	v_mov_b32_e32 v79, v6
	v_mov_b32_e32 v80, v6
	v_mov_b32_e32 v81, v6
	v_mov_b32_e32 v82, v6
	v_mov_b32_e32 v83, v6
	v_mov_b32_e32 v84, v6
	v_mov_b32_e32 v85, v6
	v_mov_b32_e32 v86, v6
	v_mov_b32_e32 v87, v6
	v_mov_b32_e32 v88, v6
	v_mov_b32_e32 v89, v6
	v_mov_b32_e32 v94, v6
	v_mov_b32_e32 v95, v6
	v_mov_b32_e32 v96, v6
	v_mov_b32_e32 v97, v6
	v_mov_b32_e32 v102, v6
	v_mov_b32_e32 v103, v6
	v_mov_b32_e32 v104, v6
	v_mov_b32_e32 v105, v6
	v_mov_b32_e32 v114, v6
	v_mov_b32_e32 v115, v6
	v_mov_b32_e32 v116, v6
	v_mov_b32_e32 v117, v6
	v_mov_b32_e32 v90, v6
	v_mov_b32_e32 v91, v6
	v_mov_b32_e32 v92, v6
	v_mov_b32_e32 v93, v6
	v_mov_b32_e32 v98, v6
	v_mov_b32_e32 v99, v6
	v_mov_b32_e32 v100, v6
	v_mov_b32_e32 v101, v6
	v_mov_b32_e32 v106, v6
	v_mov_b32_e32 v107, v6
	v_mov_b32_e32 v108, v6
	v_mov_b32_e32 v109, v6
	v_mov_b32_e32 v110, v6
	v_mov_b32_e32 v111, v6
	v_mov_b32_e32 v112, v6
	v_mov_b32_e32 v113, v6
	v_mov_b32_e32 v118, v6
	v_mov_b32_e32 v119, v6
	v_mov_b32_e32 v120, v6
	v_mov_b32_e32 v121, v6
	v_mov_b32_e32 v122, v6
	v_mov_b32_e32 v123, v6
	v_mov_b32_e32 v124, v6
	v_mov_b32_e32 v125, v6
	v_mov_b32_e32 v126, v6
	v_mov_b32_e32 v127, v6
	v_mov_b32_e32 v128, v6
	v_mov_b32_e32 v129, v6
	v_mov_b32_e32 v130, v6
	v_mov_b32_e32 v131, v6
	v_mov_b32_e32 v132, v6
	v_mov_b32_e32 v133, v6
	s_barrier
	s_branch .LBB0_270
	s_nop 0
	s_nop 0
	s_nop 0
	s_nop 0
	s_nop 0
	s_nop 0
	s_nop 0
	s_nop 0
	s_nop 0
	s_nop 0
	s_nop 0
	s_nop 0
	s_nop 0
	s_nop 0
.LBB0_268:
	s_mov_b64 s[22:23], s[24:25]
	s_mov_b64 s[4:5], s[20:21]
	s_mov_b32 s58, s59
	s_andn2_b64 vcc, exec, s[38:39]
	s_cbranch_vccz .LBB0_288
